# placement trial: P10 K-loop alone shifted by 8 bytes
# baseline (speedup 1.0000x reference)
; #define PG8_STAGE(bufoff, gbase, voff) do { _Pragma("unroll") for (int _i = 0; _i < 2; ++_i) \
;         __builtin_amdgcn_global_load_lds((const unsigned*)((const char*)(gbase) + (voff)[_i]), (PG8_LAS unsigned*)(lds + (bufoff) + ldsw + _i * 8192), 16, 0, 0); } while (0)
; #define PG8_WAIT_V(n) asm volatile("s_waitcnt vmcnt(" #n ")" ::: "memory")
; #define PG8_BAR __builtin_amdgcn_s_barrier()
; template <class Epi, class Sched, bool ALIGN_EPI = false, bool SP2 = false>
; __device__ __forceinline__ void gemm_phase(PG8_LAS unsigned char* lds, const Gemm g, const Sched& S, const Epi& E) {
;     const int tid = threadIdx.x, wid = __builtin_amdgcn_readfirstlane(tid >> 6), lane = tid & 63, wr = wid >> 2, wc = wid & 3, fr = lane & 15, fq = lane >> 4;
;     const int K = g.K, nt = K / BK;
;     unsigned voffA[2], voffB[2];
; #pragma unroll
;     for (int i = 0; i < 2; ++i) { int R, C; stage_rc(tid * 16 + i * 8192, R, C); const int Rb = Epi::PERM ? ((R & ~31) + perm32(R & 31)) : R;
;         voffA[i] = (unsigned)(R * K + C) * 2u; voffB[i] = (unsigned)(Rb * K + C) * 2u; }
;     const size_t kstep = (size_t)(BK * 2);
;     const size_t hstep = (size_t)HALF * K * 2;
;     const size_t tstep = 2 * hstep;
;     const unsigned ldsw = (unsigned)wid * 1024u;
;     const int aoff = lds_byte(wr * 64 + fr, fq * 8), boff = lds_byte(wc * 32 + fr, fq * 8);
;     ...
;     Unit cur, nxt; int ui = 0;
;     if (!S.next(0, cur)) return;
;     f32x4 acc[2][2][4][2];
; #pragma unroll
;     for (int a = 0; a < 2; ++a)
; #pragma unroll
;         for (int b = 0; b < 2; ++b)
; #pragma unroll
;             for (int m = 0; m < 4; ++m)
; #pragma unroll
;                 for (int n = 0; n < 2; ++n) acc[a][b][m][n] = (f32x4){0.f, 0.f, 0.f, 0.f};
;     bf16x8 At[4][2], B0[2][2], B1[2][2];
;     const char* cA = (const char*)g.A + (size_t)cur.pm * tstep; const char* cB = (const char*)g.Bt + (size_t)cur.pn * tstep;
;     S.a_ready(cur);
;     if constexpr (SP2) {
;         PG8_STAGE(PG8_SB(0, 0), cB, voffB); PG8_STAGE(PG8_SB(0, 1), cB + hstep, voffB); PG8_STAGE(PG8_SA(0, 0), cA, voffA); PG8_STAGE(PG8_SA(0, 1), cA + hstep, voffA);
;         if (wr == 1) PG8_BAR;
;         PG8_WAIT_V(2); PG8_BAR;
;         PG8_STAGE(PG8_SB(1, 0), cB + kstep, voffB); PG8_STAGE(PG8_SA(1, 0), cA + kstep, voffA); PG8_STAGE(PG8_SB(1, 1), cB + hstep + kstep, voffB);
.LBB0_1813:
	s_cmp_lt_i32 s84, 11
	s_cselect_b64 s[0:1], -1, 0
	s_and_b64 s[0:1], s[0:1], s[2:3]
	s_andn2_b64 vcc, exec, s[0:1]
	s_cbranch_vccnz .LBB0_1830
	s_cmpk_gt_i32 s96, 0x57f
	s_mov_b64 s[2:3], s[30:31]
	v_readfirstlane_b32 s12, v196
	s_cbranch_scc1 .LBB0_1830
	s_nop 0
	s_nop 0
	s_waitcnt lgkmcnt(0)
	v_lshrrev_b32_e32 v2, 1, v196
	v_and_b32_e32 v11, 24, v2
	v_lshrrev_b32_e32 v2, 5, v196
	v_and_b32_e32 v2, 4, v2
	v_bfe_u32 v3, v196, 2, 2
	v_lshlrev_b32_e32 v0, 4, v196
	v_and_b32_e32 v1, 32, v196
	v_bfe_u32 v10, v196, 2, 4
	v_or3_b32 v2, v2, v3, v11
	v_lshrrev_b32_e32 v3, 3, v196
	s_movk_i32 s4, 0x70
	s_add_u32 s33, s2, 0xbb00000
	v_bitop3_b32 v8, v0, v1, 48 bitop3:0x6c
	v_and_b32_e32 v9, 64, v196
	v_and_or_b32 v4, v3, s4, v10
	s_movk_i32 s4, 0x60
	v_add_u32_e32 v12, 0x2000, v0
	s_addc_u32 s38, s3, 0
	v_or_b32_e32 v1, v8, v9
	v_and_or_b32 v3, v3, s4, v2
	v_lshrrev_b32_e32 v0, 7, v12
	s_movk_i32 s4, 0xf0
	s_add_u32 s39, s2, 0x2400000
	v_lshl_or_b32 v130, v3, 11, v1
	v_and_or_b32 v3, v0, s4, v10
	s_movk_i32 s4, 0xe0
	s_addc_u32 s40, s3, 0
	s_ashr_i32 s42, s96, 31
	v_and_or_b32 v0, v0, s4, v2
	s_lshr_b32 s4, s42, 29
	s_add_i32 s4, s96, s4
	s_lshr_b32 s10, s12, 6
	s_ashr_i32 s5, s4, 3
	s_and_b32 s4, s4, -8
	s_lshr_b32 s13, s12, 8
	s_lshl_b32 s41, s10, 10
	s_sub_i32 s4, s96, s4
	s_cmp_lt_i32 s4, 0
	s_movk_i32 s43, 0xb1
	s_cselect_b32 s6, s43, 0xb0
	s_mul_i32 s4, s4, s6
	s_add_i32 s4, s4, s5
	s_mul_hi_i32 s5, s4, 0x2e8ba2e9
	s_lshr_b32 s6, s5, 31
	s_ashr_i32 s5, s5, 5
	s_add_i32 s5, s5, s6
	s_lshl_b32 s6, s5, 3
	s_mulk_i32 s5, 0xb0
	s_sub_i32 s4, s4, s5
	s_sext_i32_i16 s5, s4
	s_bfe_u32 s5, s5, 0x3001c
	s_add_i32 s5, s4, s5
	s_sext_i32_i16 s7, s5
	s_and_b32 s5, s5, 0xfff8
	s_sub_i32 s4, s4, s5
	s_sext_i32_i16 s4, s4
	s_lshr_b32 s14, s7, 3
	s_add_i32 s24, s6, s4
	s_add_u32 s8, s2, 0x3700000
	s_addc_u32 s9, s3, 0
	v_and_b32_e32 v228, 15, v196
	v_lshrrev_b32_e32 v229, 8, v196
	v_lshl_or_b32 v228, v229, 6, v228
	v_lshl_add_u32 v228, s24, 8, v228
	v_mov_b32_e32 v229, 0
	v_lshl_add_u64 v[228:229], v[228:229], 2, s[8:9]
	global_load_dword v230, v[228:229], off
	global_load_dword v231, v[228:229], off offset:64
	global_load_dword v232, v[228:229], off offset:128
	global_load_dword v233, v[228:229], off offset:192
	global_load_dword v234, v[228:229], off offset:512
	global_load_dword v235, v[228:229], off offset:576
	global_load_dword v236, v[228:229], off offset:640
	global_load_dword v237, v[228:229], off offset:704
	s_ashr_i32 s25, s24, 31
	s_bfe_i64 s[6:7], s[14:15], 0x100000
	s_lshl_b64 s[4:5], s[24:25], 19
	s_lshl_b64 s[6:7], s[6:7], 19
	s_add_u32 s26, s39, s6
	s_addc_u32 s27, s40, s7
	s_add_i32 s25, s41, 0
	s_add_i32 m0, s25, 0x10000
	v_lshl_or_b32 v134, v0, 11, v1
	global_load_lds_dwordx4 v130, s[26:27]
	s_add_i32 m0, s25, 0x12000
	s_add_u32 s6, s26, 0x40000
	global_load_lds_dwordx4 v134, s[26:27]
	s_addc_u32 s7, s27, 0
	s_add_i32 m0, s25, 0x14000
	v_lshl_or_b32 v128, v4, 11, v1
	global_load_lds_dwordx4 v130, s[6:7]
	s_add_i32 m0, s25, 0x16000
	s_add_u32 s34, s33, s4
	s_addc_u32 s35, s38, s5
	s_add_i32 s44, s25, 0x2000
	global_load_lds_dwordx4 v134, s[6:7]
	s_mov_b32 m0, s25
	s_add_u32 s4, s34, 0x40000
	v_lshl_or_b32 v132, v3, 11, v1
	global_load_lds_dwordx4 v128, s[34:35]
	s_mov_b32 m0, s44
	s_addc_u32 s5, s35, 0
	s_add_i32 s45, s25, 0x4000
	global_load_lds_dwordx4 v132, s[34:35]
	s_mov_b32 m0, s45
	s_add_i32 s46, s25, 0x6000
	global_load_lds_dwordx4 v128, s[4:5]
	s_mov_b32 m0, s46
	v_mov_b32_e32 v131, 0
	global_load_lds_dwordx4 v132, s[4:5]
	v_mov_b32_e32 v135, v131
	v_mov_b32_e32 v129, v131
	v_mov_b32_e32 v133, v131
	s_cmp_eq_u32 s13, 1
	s_mov_b32 s47, 0
	v_lshl_add_u64 v[6:7], s[26:27], 0, v[130:131]
	v_lshl_add_u64 v[4:5], s[26:27], 0, v[134:135]
	v_lshl_add_u64 v[0:1], s[34:35], 0, v[128:129]
	s_cselect_b64 s[4:5], -1, 0
	s_cmp_lg_u32 s13, 1
	v_lshl_add_u64 v[2:3], s[34:35], 0, v[132:133]
	s_cbranch_scc1 .LBB0_1817
	s_barrier

; #define PG8_STAGE(bufoff, gbase, voff) do { _Pragma("unroll") for (int _i = 0; _i < 2; ++_i) \
;         __builtin_amdgcn_global_load_lds((const unsigned*)((const char*)(gbase) + (voff)[_i]), (PG8_LAS unsigned*)(lds + (bufoff) + ldsw + _i * 8192), 16, 0, 0); } while (0)
; #define PG8_LDA(dst, b, h) do { _Pragma("unroll") for (int m = 0; m < 4; ++m) _Pragma("unroll") for (int k = 0; k < 2; ++k) dst[m][k] = *(const PG8_LAS bf16x8*)(lds + PG8_SA(b, h) + aoff + m * 2048 + k * 1024); } while (0)
; #define PG8_LDB(dst, b, h) do { _Pragma("unroll") for (int n = 0; n < 2; ++n) _Pragma("unroll") for (int k = 0; k < 2; ++k) dst[n][k] = *(const PG8_LAS bf16x8*)(lds + PG8_SB(b, h) + boff + n * 2048 + k * 1024); } while (0)
; #define PG8_MMA(ai, bj, At, Bt) do { __builtin_amdgcn_s_setprio(1); _Pragma("unroll") for (int m = 0; m < 4; ++m) _Pragma("unroll") for (int n = 0; n < 2; ++n) _Pragma("unroll") for (int k = 0; k < 2; ++k) \
;         acc[ai][bj][m][n] = __builtin_amdgcn_mfma_f32_16x16x32_bf16(Bt[n][k], At[m][k], acc[ai][bj][m][n], 0, 0, 0); __builtin_amdgcn_s_setprio(0); } while (0)
; #define PG8_WAIT_V(n) asm volatile("s_waitcnt vmcnt(" #n ")" ::: "memory")
; #define PG8_WAIT_L(n) asm volatile("s_waitcnt lgkmcnt(" #n ")" ::: "memory")
; #define PG8_BAR __builtin_amdgcn_s_barrier()
; #define PG8_SCHED __builtin_amdgcn_sched_barrier(0)
; template <class Epi, class Sched, bool ALIGN_EPI = false, bool SP2 = false>
; __device__ __forceinline__ void gemm_phase(PG8_LAS unsigned char* lds, const Gemm g, const Sched& S, const Epi& E) {
;     ...
;             PG8_LDB(B0, 0, 0); PG8_LDB(B1, 0, 1); PG8_SCHED; PG8_LDA(At, 0, 0); PG8_STAGE(PG8_SA(1, 1), a1 + hstep, voffA);
;             PG8_WAIT_V(8); PG8_WAIT_L(0); PG8_BAR; PG8_MMA(0, 0, At, B0); PG8_MMA(0, 1, At, B1); PG8_BAR; PG8_SCHED;
;             PG8_LDA(At, 0, 1); PG8_STAGE(PG8_SB(0, 0), b2, voffB); PG8_STAGE(PG8_SB(0, 1), b2 + hstep, voffB); PG8_STAGE(PG8_SA(0, 0), a2, voffA);
;             PG8_WAIT_V(8); PG8_WAIT_L(0); PG8_BAR; PG8_MMA(1, 0, At, B0); PG8_MMA(1, 1, At, B1); PG8_BAR; PG8_SCHED;
.LBB0_1823:
	ds_read_b128 v[144:147], v155
	ds_read_b128 v[148:151], v155 offset:1024
	ds_read_b128 v[160:163], v155 offset:2048
	ds_read_b128 v[164:167], v155 offset:3072
	ds_read_b128 v[168:171], v156
	ds_read_b128 v[172:175], v156 offset:1024
	ds_read_b128 v[176:179], v156 offset:2048
	ds_read_b128 v[180:183], v156 offset:3072
	s_add_u32 s34, s26, 0xfffc0080
	s_addc_u32 s35, s27, -1
	s_cmp_eq_u32 s58, 12
	s_cselect_b32 s37, s12, s35
	s_cselect_b32 s36, s13, s34
	s_cselect_b32 s35, s17, s57
	s_cselect_b32 s34, s19, s56
	v_lshl_add_u64 v[218:219], s[26:27], 0, v[138:139]
	s_add_i32 m0, s25, 0xc000
	ds_read_b128 v[184:187], v157
	ds_read_b128 v[188:191], v157 offset:1024
	ds_read_b128 v[192:195], v157 offset:2048
	ds_read_b128 v[198:201], v157 offset:3072
	ds_read_b128 v[202:205], v157 offset:4096
	ds_read_b128 v[206:209], v157 offset:5120
	ds_read_b128 v[210:213], v157 offset:6144
	ds_read_b128 v[214:217], v157 offset:7168
	global_load_lds_dwordx4 v[218:219], off
	v_lshl_add_u64 v[218:219], s[26:27], 0, v[136:137]
	s_add_i32 m0, s25, 0xe000
	s_nop 0
	global_load_lds_dwordx4 v[218:219], off
	s_waitcnt vmcnt(8)
	s_waitcnt lgkmcnt(0)
	s_barrier
	s_setprio 1
	s_waitcnt lgkmcnt(0)
	v_mfma_f32_16x16x32_bf16 v[124:127], v[144:147], v[184:187], v[124:127]
	v_mfma_f32_16x16x32_bf16 v[120:123], v[160:163], v[184:187], v[120:123]
	v_mfma_f32_16x16x32_bf16 v[108:111], v[144:147], v[192:195], v[108:111]
	v_mfma_f32_16x16x32_bf16 v[104:107], v[160:163], v[192:195], v[104:107]
	v_mfma_f32_16x16x32_bf16 v[92:95], v[144:147], v[202:205], v[92:95]
	v_mfma_f32_16x16x32_bf16 v[88:91], v[160:163], v[202:205], v[88:91]
	v_mfma_f32_16x16x32_bf16 v[76:79], v[144:147], v[210:213], v[76:79]
	v_mfma_f32_16x16x32_bf16 v[72:75], v[160:163], v[210:213], v[72:75]
	v_mfma_f32_16x16x32_bf16 v[124:127], v[148:151], v[188:191], v[124:127]
	v_mfma_f32_16x16x32_bf16 v[120:123], v[164:167], v[188:191], v[120:123]
	v_mfma_f32_16x16x32_bf16 v[108:111], v[148:151], v[198:201], v[108:111]
	v_mfma_f32_16x16x32_bf16 v[104:107], v[164:167], v[198:201], v[104:107]
	v_mfma_f32_16x16x32_bf16 v[92:95], v[148:151], v[206:209], v[92:95]
	v_mfma_f32_16x16x32_bf16 v[88:91], v[164:167], v[206:209], v[88:91]
	v_mfma_f32_16x16x32_bf16 v[76:79], v[148:151], v[214:217], v[76:79]
	v_mfma_f32_16x16x32_bf16 v[72:75], v[164:167], v[214:217], v[72:75]
	s_setprio 0
	s_setprio 1
	v_mfma_f32_16x16x32_bf16 v[116:119], v[168:171], v[184:187], v[116:119]
	v_mfma_f32_16x16x32_bf16 v[112:115], v[176:179], v[184:187], v[112:115]
	v_mfma_f32_16x16x32_bf16 v[100:103], v[168:171], v[192:195], v[100:103]
	v_mfma_f32_16x16x32_bf16 v[96:99], v[176:179], v[192:195], v[96:99]
	v_mfma_f32_16x16x32_bf16 v[84:87], v[168:171], v[202:205], v[84:87]
	v_mfma_f32_16x16x32_bf16 v[80:83], v[176:179], v[202:205], v[80:83]
	v_mfma_f32_16x16x32_bf16 v[68:71], v[168:171], v[210:213], v[68:71]
	v_mfma_f32_16x16x32_bf16 v[64:67], v[176:179], v[210:213], v[64:67]
	v_mfma_f32_16x16x32_bf16 v[116:119], v[172:175], v[188:191], v[116:119]
	v_mfma_f32_16x16x32_bf16 v[112:115], v[180:183], v[188:191], v[112:115]
	v_mfma_f32_16x16x32_bf16 v[100:103], v[172:175], v[198:201], v[100:103]
	v_mfma_f32_16x16x32_bf16 v[96:99], v[180:183], v[198:201], v[96:99]
	v_mfma_f32_16x16x32_bf16 v[84:87], v[172:175], v[206:209], v[84:87]
	v_mfma_f32_16x16x32_bf16 v[80:83], v[180:183], v[206:209], v[80:83]
	v_mfma_f32_16x16x32_bf16 v[68:71], v[172:175], v[214:217], v[68:71]
	v_mfma_f32_16x16x32_bf16 v[64:67], v[180:183], v[214:217], v[64:67]
	s_setprio 0
	s_barrier
	s_add_i32 s59, s52, s41
	v_lshl_add_u64 v[218:219], s[34:35], 0, v[130:131]
	s_mov_b32 m0, s59
	ds_read_b128 v[184:187], v157 offset:16384
	ds_read_b128 v[188:191], v157 offset:17408
	ds_read_b128 v[192:195], v157 offset:18432
	ds_read_b128 v[198:201], v157 offset:19456
	ds_read_b128 v[202:205], v157 offset:20480
	ds_read_b128 v[206:209], v157 offset:21504
	ds_read_b128 v[210:213], v157 offset:22528
	ds_read_b128 v[214:217], v157 offset:23552
	global_load_lds_dwordx4 v[218:219], off
	s_add_i32 m0, s59, 0x2000
	s_add_u32 s60, s34, 0x40000
	v_lshl_add_u64 v[220:221], s[34:35], 0, v[134:135]
	s_addc_u32 s61, s35, 0
	s_add_i32 s59, s53, s41
	global_load_lds_dwordx4 v[220:221], off
	v_lshl_add_u64 v[222:223], s[60:61], 0, v[130:131]
	s_mov_b32 m0, s59
	v_lshl_add_u64 v[224:225], s[36:37], 0, v[132:133]
	global_load_lds_dwordx4 v[222:223], off
	v_lshl_add_u64 v[222:223], s[60:61], 0, v[134:135]
	s_add_i32 m0, s59, 0x2000
	s_nop 0
	global_load_lds_dwordx4 v[222:223], off
	v_lshl_add_u64 v[222:223], s[36:37], 0, v[128:129]
	s_mov_b32 m0, s25
	s_nop 0
	global_load_lds_dwordx4 v[222:223], off
	s_mov_b32 m0, s44
	s_nop 0
	global_load_lds_dwordx4 v[224:225], off
	s_waitcnt vmcnt(8)
	s_waitcnt lgkmcnt(0)
	s_barrier
; #define PG8_STAGE(bufoff, gbase, voff) do { _Pragma("unroll") for (int _i = 0; _i < 2; ++_i) \
;         __builtin_amdgcn_global_load_lds((const unsigned*)((const char*)(gbase) + (voff)[_i]), (PG8_LAS unsigned*)(lds + (bufoff) + ldsw + _i * 8192), 16, 0, 0); } while (0)
; #define PG8_LDA(dst, b, h) do { _Pragma("unroll") for (int m = 0; m < 4; ++m) _Pragma("unroll") for (int k = 0; k < 2; ++k) dst[m][k] = *(const PG8_LAS bf16x8*)(lds + PG8_SA(b, h) + aoff + m * 2048 + k * 1024); } while (0)
; #define PG8_LDB(dst, b, h) do { _Pragma("unroll") for (int n = 0; n < 2; ++n) _Pragma("unroll") for (int k = 0; k < 2; ++k) dst[n][k] = *(const PG8_LAS bf16x8*)(lds + PG8_SB(b, h) + boff + n * 2048 + k * 1024); } while (0)
; #define PG8_MMA(ai, bj, At, Bt) do { __builtin_amdgcn_s_setprio(1); _Pragma("unroll") for (int m = 0; m < 4; ++m) _Pragma("unroll") for (int n = 0; n < 2; ++n) _Pragma("unroll") for (int k = 0; k < 2; ++k) \
;         acc[ai][bj][m][n] = __builtin_amdgcn_mfma_f32_16x16x32_bf16(Bt[n][k], At[m][k], acc[ai][bj][m][n], 0, 0, 0); __builtin_amdgcn_s_setprio(0); } while (0)
; #define PG8_WAIT_V(n) asm volatile("s_waitcnt vmcnt(" #n ")" ::: "memory")
; #define PG8_WAIT_L(n) asm volatile("s_waitcnt lgkmcnt(" #n ")" ::: "memory")
; #define PG8_BAR __builtin_amdgcn_s_barrier()
; #define PG8_SCHED __builtin_amdgcn_sched_barrier(0)
; template <class Epi, class Sched, bool ALIGN_EPI = false, bool SP2 = false>
; __device__ __forceinline__ void gemm_phase(PG8_LAS unsigned char* lds, const Gemm g, const Sched& S, const Epi& E) {
;     ...
;             PG8_WAIT_V(8); PG8_WAIT_L(0); PG8_BAR; PG8_MMA(1, 0, At, B0); PG8_MMA(1, 1, At, B1); PG8_BAR; PG8_SCHED;
;             PG8_LDB(B0, 1, 0); PG8_LDB(B1, 1, 1); PG8_SCHED; PG8_LDA(At, 1, 0); PG8_STAGE(PG8_SA(0, 1), a2 + hstep, voffA);
;             PG8_WAIT_V(8); PG8_WAIT_L(0); PG8_BAR; PG8_MMA(0, 0, At, B0); PG8_MMA(0, 1, At, B1); PG8_BAR; PG8_SCHED;
	s_setprio 1
	s_waitcnt lgkmcnt(0)
	v_mfma_f32_16x16x32_bf16 v[60:63], v[144:147], v[184:187], v[60:63]
	v_mfma_f32_16x16x32_bf16 v[56:59], v[160:163], v[184:187], v[56:59]
	v_mfma_f32_16x16x32_bf16 v[44:47], v[144:147], v[192:195], v[44:47]
	v_mfma_f32_16x16x32_bf16 v[40:43], v[160:163], v[192:195], v[40:43]
	v_mfma_f32_16x16x32_bf16 v[28:31], v[144:147], v[202:205], v[28:31]
	v_mfma_f32_16x16x32_bf16 v[24:27], v[160:163], v[202:205], v[24:27]
	v_mfma_f32_16x16x32_bf16 v[12:15], v[144:147], v[210:213], v[12:15]
	v_mfma_f32_16x16x32_bf16 v[8:11], v[160:163], v[210:213], v[8:11]
	v_mfma_f32_16x16x32_bf16 v[60:63], v[148:151], v[188:191], v[60:63]
	v_mfma_f32_16x16x32_bf16 v[56:59], v[164:167], v[188:191], v[56:59]
	v_mfma_f32_16x16x32_bf16 v[44:47], v[148:151], v[198:201], v[44:47]
	v_mfma_f32_16x16x32_bf16 v[40:43], v[164:167], v[198:201], v[40:43]
	v_mfma_f32_16x16x32_bf16 v[28:31], v[148:151], v[206:209], v[28:31]
	v_mfma_f32_16x16x32_bf16 v[24:27], v[164:167], v[206:209], v[24:27]
	v_mfma_f32_16x16x32_bf16 v[12:15], v[148:151], v[214:217], v[12:15]
	v_mfma_f32_16x16x32_bf16 v[8:11], v[164:167], v[214:217], v[8:11]
	s_setprio 0
	s_setprio 1
	v_mfma_f32_16x16x32_bf16 v[52:55], v[168:171], v[184:187], v[52:55]
	v_mfma_f32_16x16x32_bf16 v[48:51], v[176:179], v[184:187], v[48:51]
	v_mfma_f32_16x16x32_bf16 v[36:39], v[168:171], v[192:195], v[36:39]
	v_mfma_f32_16x16x32_bf16 v[32:35], v[176:179], v[192:195], v[32:35]
	v_mfma_f32_16x16x32_bf16 v[20:23], v[168:171], v[202:205], v[20:23]
	v_mfma_f32_16x16x32_bf16 v[16:19], v[176:179], v[202:205], v[16:19]
	v_mfma_f32_16x16x32_bf16 v[4:7], v[168:171], v[210:213], v[4:7]
	v_mfma_f32_16x16x32_bf16 v[0:3], v[176:179], v[210:213], v[0:3]
	v_mfma_f32_16x16x32_bf16 v[52:55], v[172:175], v[188:191], v[52:55]
	v_mfma_f32_16x16x32_bf16 v[48:51], v[180:183], v[188:191], v[48:51]
	v_mfma_f32_16x16x32_bf16 v[36:39], v[172:175], v[198:201], v[36:39]
	v_mfma_f32_16x16x32_bf16 v[32:35], v[180:183], v[198:201], v[32:35]
	v_mfma_f32_16x16x32_bf16 v[20:23], v[172:175], v[206:209], v[20:23]
	v_mfma_f32_16x16x32_bf16 v[16:19], v[180:183], v[206:209], v[16:19]
	v_mfma_f32_16x16x32_bf16 v[4:7], v[172:175], v[214:217], v[4:7]
	v_mfma_f32_16x16x32_bf16 v[0:3], v[180:183], v[214:217], v[0:3]
	s_setprio 0
	s_barrier
	s_add_i32 s59, 0, 0x18000
	v_add_u32_e32 v159, s59, v153
	s_add_i32 s60, 0, 0x1c000
	ds_read_b128 v[144:147], v159
	ds_read_b128 v[148:151], v159 offset:1024
	ds_read_b128 v[160:163], v159 offset:2048
	ds_read_b128 v[164:167], v159 offset:3072
	v_add_u32_e32 v159, s60, v153
	ds_read_b128 v[168:171], v159
	ds_read_b128 v[172:175], v159 offset:1024
	ds_read_b128 v[176:179], v159 offset:2048
	ds_read_b128 v[180:183], v159 offset:3072
	s_add_u32 s36, s36, 0x40000
	s_addc_u32 s37, s37, 0
	s_mov_b32 m0, s45
	v_lshl_add_u64 v[226:227], s[36:37], 0, v[128:129]
	ds_read_b128 v[184:187], v157 offset:32768
	ds_read_b128 v[188:191], v157 offset:33792
	ds_read_b128 v[192:195], v157 offset:34816
	ds_read_b128 v[198:201], v157 offset:35840
	ds_read_b128 v[202:205], v157 offset:36864
	ds_read_b128 v[206:209], v157 offset:37888
	ds_read_b128 v[210:213], v157 offset:38912
	ds_read_b128 v[214:217], v157 offset:39936
	global_load_lds_dwordx4 v[226:227], off
	v_lshl_add_u64 v[226:227], s[36:37], 0, v[132:133]
	s_mov_b32 m0, s46
	s_nop 0
	global_load_lds_dwordx4 v[226:227], off
	s_waitcnt vmcnt(8)
	s_waitcnt lgkmcnt(0)
	s_barrier
	s_setprio 1
	s_waitcnt lgkmcnt(0)
	v_mfma_f32_16x16x32_bf16 v[124:127], v[144:147], v[184:187], v[124:127]
	v_mfma_f32_16x16x32_bf16 v[120:123], v[160:163], v[184:187], v[120:123]
	v_mfma_f32_16x16x32_bf16 v[108:111], v[144:147], v[192:195], v[108:111]
	v_mfma_f32_16x16x32_bf16 v[104:107], v[160:163], v[192:195], v[104:107]
	v_mfma_f32_16x16x32_bf16 v[92:95], v[144:147], v[202:205], v[92:95]
	v_mfma_f32_16x16x32_bf16 v[88:91], v[160:163], v[202:205], v[88:91]
	v_mfma_f32_16x16x32_bf16 v[76:79], v[144:147], v[210:213], v[76:79]
	v_mfma_f32_16x16x32_bf16 v[72:75], v[160:163], v[210:213], v[72:75]
	v_mfma_f32_16x16x32_bf16 v[124:127], v[148:151], v[188:191], v[124:127]
	v_mfma_f32_16x16x32_bf16 v[120:123], v[164:167], v[188:191], v[120:123]
	v_mfma_f32_16x16x32_bf16 v[108:111], v[148:151], v[198:201], v[108:111]
	v_mfma_f32_16x16x32_bf16 v[104:107], v[164:167], v[198:201], v[104:107]
	v_mfma_f32_16x16x32_bf16 v[92:95], v[148:151], v[206:209], v[92:95]
	v_mfma_f32_16x16x32_bf16 v[88:91], v[164:167], v[206:209], v[88:91]
	v_mfma_f32_16x16x32_bf16 v[76:79], v[148:151], v[214:217], v[76:79]
	v_mfma_f32_16x16x32_bf16 v[72:75], v[164:167], v[214:217], v[72:75]
	s_setprio 0
	s_setprio 1
	v_mfma_f32_16x16x32_bf16 v[116:119], v[168:171], v[184:187], v[116:119]
	v_mfma_f32_16x16x32_bf16 v[112:115], v[176:179], v[184:187], v[112:115]
	v_mfma_f32_16x16x32_bf16 v[100:103], v[168:171], v[192:195], v[100:103]
	v_mfma_f32_16x16x32_bf16 v[96:99], v[176:179], v[192:195], v[96:99]
	v_mfma_f32_16x16x32_bf16 v[84:87], v[168:171], v[202:205], v[84:87]
	v_mfma_f32_16x16x32_bf16 v[80:83], v[176:179], v[202:205], v[80:83]
	v_mfma_f32_16x16x32_bf16 v[68:71], v[168:171], v[210:213], v[68:71]
	v_mfma_f32_16x16x32_bf16 v[64:67], v[176:179], v[210:213], v[64:67]
	v_mfma_f32_16x16x32_bf16 v[116:119], v[172:175], v[188:191], v[116:119]
	v_mfma_f32_16x16x32_bf16 v[112:115], v[180:183], v[188:191], v[112:115]
	v_mfma_f32_16x16x32_bf16 v[100:103], v[172:175], v[198:201], v[100:103]
	v_mfma_f32_16x16x32_bf16 v[96:99], v[180:183], v[198:201], v[96:99]
	v_mfma_f32_16x16x32_bf16 v[84:87], v[172:175], v[206:209], v[84:87]
	v_mfma_f32_16x16x32_bf16 v[80:83], v[180:183], v[206:209], v[80:83]
	v_mfma_f32_16x16x32_bf16 v[68:71], v[172:175], v[214:217], v[68:71]
	v_mfma_f32_16x16x32_bf16 v[64:67], v[180:183], v[214:217], v[64:67]
	s_setprio 0
	s_barrier
; #define PG8_STAGE(bufoff, gbase, voff) do { _Pragma("unroll") for (int _i = 0; _i < 2; ++_i) \
;         __builtin_amdgcn_global_load_lds((const unsigned*)((const char*)(gbase) + (voff)[_i]), (PG8_LAS unsigned*)(lds + (bufoff) + ldsw + _i * 8192), 16, 0, 0); } while (0)
; #define PG8_LDA(dst, b, h) do { _Pragma("unroll") for (int m = 0; m < 4; ++m) _Pragma("unroll") for (int k = 0; k < 2; ++k) dst[m][k] = *(const PG8_LAS bf16x8*)(lds + PG8_SA(b, h) + aoff + m * 2048 + k * 1024); } while (0)
; #define PG8_LDB(dst, b, h) do { _Pragma("unroll") for (int n = 0; n < 2; ++n) _Pragma("unroll") for (int k = 0; k < 2; ++k) dst[n][k] = *(const PG8_LAS bf16x8*)(lds + PG8_SB(b, h) + boff + n * 2048 + k * 1024); } while (0)
; template <class Epi, class Sched, bool ALIGN_EPI = false, bool SP2 = false>
; __device__ __forceinline__ void gemm_phase(PG8_LAS unsigned char* lds, const Gemm g, const Sched& S, const Epi& E) {
;     ...
;         for (int t = 0; t < nt; t += 2) {
;             const bool last = (t == nt - 2);
;             const char* a1 = cA + (size_t)(t + 1) * kstep;
;             const char* a2 = last ? nA : cA + (size_t)(t + 2) * kstep; const char* b2 = last ? nB : cB + (size_t)(t + 2) * kstep;
;             const char* a3 = a2 + kstep; const char* b3 = b2 + kstep;
;             if (last && has_next) S.a_ready(nxt);
;             if constexpr (SP2) {
;             PG8_LDB(B0, 0, 0); PG8_LDB(B1, 0, 1); PG8_SCHED; PG8_LDA(At, 0, 0); PG8_STAGE(PG8_SA(1, 1), a1 + hstep, voffA);
;             PG8_WAIT_V(8); PG8_WAIT_L(0); PG8_BAR; PG8_MMA(0, 0, At, B0); PG8_MMA(0, 1, At, B1); PG8_BAR; PG8_SCHED;
;             PG8_LDA(At, 0, 1); PG8_STAGE(PG8_SB(0, 0), b2, voffB); PG8_STAGE(PG8_SB(0, 1), b2 + hstep, voffB); PG8_STAGE(PG8_SA(0, 0), a2, voffA);
;             PG8_WAIT_V(8); PG8_WAIT_L(0); PG8_BAR; PG8_MMA(1, 0, At, B0); PG8_MMA(1, 1, At, B1); PG8_BAR; PG8_SCHED;
;             PG8_LDB(B0, 1, 0); PG8_LDB(B1, 1, 1); PG8_SCHED; PG8_LDA(At, 1, 0); PG8_STAGE(PG8_SA(0, 1), a2 + hstep, voffA);
;             PG8_WAIT_V(8); PG8_WAIT_L(0); PG8_BAR; PG8_MMA(0, 0, At, B0); PG8_MMA(0, 1, At, B1); PG8_BAR; PG8_SCHED;
;             PG8_LDA(At, 1, 1); PG8_STAGE(PG8_SB(1, 0), b3, voffB); PG8_STAGE(PG8_SB(1, 1), b3 + hstep, voffB); PG8_STAGE(PG8_SA(1, 0), a3, voffA);
;             PG8_WAIT_V(8); PG8_WAIT_L(0); PG8_BAR; PG8_MMA(1, 0, At, B0); PG8_MMA(1, 1, At, B1); PG8_BAR; PG8_SCHED;
	s_add_i32 s36, s59, s41
	v_lshl_add_u64 v[218:219], v[218:219], 0, s[10:11]
	s_mov_b32 m0, s36
	ds_read_b128 v[184:187], v157 offset:49152
	ds_read_b128 v[188:191], v157 offset:50176
	ds_read_b128 v[192:195], v157 offset:51200
	ds_read_b128 v[198:201], v157 offset:52224
	ds_read_b128 v[202:205], v157 offset:53248
	ds_read_b128 v[206:209], v157 offset:54272
	ds_read_b128 v[210:213], v157 offset:55296
	ds_read_b128 v[214:217], v157 offset:56320
	global_load_lds_dwordx4 v[218:219], off
	s_add_i32 m0, s36, 0x2000
	s_add_u32 s34, s34, 0x40080
	v_lshl_add_u64 v[218:219], v[220:221], 0, s[10:11]
	s_addc_u32 s35, s35, 0
	s_add_i32 s36, s60, s41
	global_load_lds_dwordx4 v[218:219], off
	v_lshl_add_u64 v[218:219], s[34:35], 0, v[130:131]
	s_mov_b32 m0, s36
	s_nop 0
	global_load_lds_dwordx4 v[218:219], off
	v_lshl_add_u64 v[218:219], s[34:35], 0, v[134:135]
	s_add_i32 m0, s36, 0x2000
	s_nop 0
	global_load_lds_dwordx4 v[218:219], off
	v_lshl_add_u64 v[218:219], v[222:223], 0, s[10:11]
	s_mov_b32 m0, s49
	s_nop 0
	global_load_lds_dwordx4 v[218:219], off
	v_lshl_add_u64 v[218:219], v[224:225], 0, s[10:11]
	s_mov_b32 m0, s50
	s_nop 0
	global_load_lds_dwordx4 v[218:219], off
	s_waitcnt vmcnt(8)
	s_waitcnt lgkmcnt(0)
	s_barrier
	s_setprio 1
	s_waitcnt lgkmcnt(0)
	v_mfma_f32_16x16x32_bf16 v[60:63], v[144:147], v[184:187], v[60:63]
	v_mfma_f32_16x16x32_bf16 v[56:59], v[160:163], v[184:187], v[56:59]
	v_mfma_f32_16x16x32_bf16 v[44:47], v[144:147], v[192:195], v[44:47]
	v_mfma_f32_16x16x32_bf16 v[40:43], v[160:163], v[192:195], v[40:43]
	v_mfma_f32_16x16x32_bf16 v[28:31], v[144:147], v[202:205], v[28:31]
	v_mfma_f32_16x16x32_bf16 v[24:27], v[160:163], v[202:205], v[24:27]
	v_mfma_f32_16x16x32_bf16 v[12:15], v[144:147], v[210:213], v[12:15]
	v_mfma_f32_16x16x32_bf16 v[8:11], v[160:163], v[210:213], v[8:11]
	v_mfma_f32_16x16x32_bf16 v[60:63], v[148:151], v[188:191], v[60:63]
	v_mfma_f32_16x16x32_bf16 v[56:59], v[164:167], v[188:191], v[56:59]
	v_mfma_f32_16x16x32_bf16 v[44:47], v[148:151], v[198:201], v[44:47]
	v_mfma_f32_16x16x32_bf16 v[40:43], v[164:167], v[198:201], v[40:43]
	v_mfma_f32_16x16x32_bf16 v[28:31], v[148:151], v[206:209], v[28:31]
	v_mfma_f32_16x16x32_bf16 v[24:27], v[164:167], v[206:209], v[24:27]
	v_mfma_f32_16x16x32_bf16 v[12:15], v[148:151], v[214:217], v[12:15]
	v_mfma_f32_16x16x32_bf16 v[8:11], v[164:167], v[214:217], v[8:11]
	s_setprio 0
	s_setprio 1
	v_mfma_f32_16x16x32_bf16 v[52:55], v[168:171], v[184:187], v[52:55]
	v_mfma_f32_16x16x32_bf16 v[48:51], v[176:179], v[184:187], v[48:51]
	v_mfma_f32_16x16x32_bf16 v[36:39], v[168:171], v[192:195], v[36:39]
	v_mfma_f32_16x16x32_bf16 v[32:35], v[176:179], v[192:195], v[32:35]
	v_mfma_f32_16x16x32_bf16 v[20:23], v[168:171], v[202:205], v[20:23]
	v_mfma_f32_16x16x32_bf16 v[16:19], v[176:179], v[202:205], v[16:19]
	v_mfma_f32_16x16x32_bf16 v[4:7], v[168:171], v[210:213], v[4:7]
	v_mfma_f32_16x16x32_bf16 v[0:3], v[176:179], v[210:213], v[0:3]
	v_mfma_f32_16x16x32_bf16 v[52:55], v[172:175], v[188:191], v[52:55]
	v_mfma_f32_16x16x32_bf16 v[48:51], v[180:183], v[188:191], v[48:51]
	v_mfma_f32_16x16x32_bf16 v[36:39], v[172:175], v[198:201], v[36:39]
	v_mfma_f32_16x16x32_bf16 v[32:35], v[180:183], v[198:201], v[32:35]
	v_mfma_f32_16x16x32_bf16 v[20:23], v[172:175], v[206:209], v[20:23]
	v_mfma_f32_16x16x32_bf16 v[16:19], v[180:183], v[206:209], v[16:19]
	v_mfma_f32_16x16x32_bf16 v[4:7], v[172:175], v[214:217], v[4:7]
	v_mfma_f32_16x16x32_bf16 v[0:3], v[180:183], v[214:217], v[0:3]
	s_setprio 0
	s_barrier
	s_add_i32 s58, s58, 2
	s_add_u32 s56, s56, 0x100
	s_addc_u32 s57, s57, 0
	s_add_u32 s26, s26, 0x100
	s_addc_u32 s27, s27, 0
	s_cmp_gt_u32 s58, 13
	s_cbranch_scc0 .LBB0_1823
	s_nop 0
	s_nop 0
	s_nop 0
	s_nop 0
	s_nop 0
	s_nop 0
	s_and_b64 vcc, exec, s[14:15]
	s_cbranch_vccz .LBB0_1826
	s_barrier
